# speedup vs baseline: 1.0231x; 1.0058x over previous
; __device__ __forceinline__ void tconv_tile(const float* __restrict__ src, int ldsrc, const float* __restrict__ gain, u16* __restrict__ dst, int dld,
;                                            int drow, int scol, int k0, int tid) {
;     ...
;   __syncthreads();
; #pragma unroll
;   for (int i = 0; i < 4; ++i) {
;     const int e = tid + i * NTHR, nn = e >> 5, kk = (e & 31) * 2;
;     *reinterpret_cast<unsigned*>(dst + (long)(drow + nn) * dld + k0 + kk) = cvtpk(tile[kk * 65 + nn], tile[(kk + 1) * 65 + nn]);
;   }
; __global__ void __launch_bounds__(NTHR, 2) mega(Params p) {
;     ...
;     for (int t = bid; t < 2 * 4480; t += nblk) {
;       const int l = t / 4480; int r = t % 4480;
;       u16* Wl = Wall + (size_t)l * W_LAYER;
;       const float* srcp; int ldsrc, K, dld, drow0 = 0, scol0 = 0, gu = 0; const float* gain = nullptr; u16* dst;
;       const float* win = p.w_in + (size_t)l * 1024 * 4800;
;       if (r < 176)            { srcp = win; ldsrc = 4800; K = 1024; gain = p.attn_norm + l * 1024; dst = Wl + W_W1; dld = 1024; drow0 = 0; scol0 = 0; }
;       else if ((r -= 176) < 128)  { srcp = win; ldsrc = 4800; K = 1024; gain = p.attn_norm + l * 1024; dst = Wl + W_W1; dld = 1024; drow0 = 704; scol0 = 1216; }
;       else if ((r -= 128) < 768)  { srcp = win; ldsrc = 4800; K = 1024; gain = p.attn_norm + l * 1024; dst = Wl + W_W1; dld = 1024; drow0 = 2304; scol0 = 1728; }
;       else if ((r -= 768) < 144)  { srcp = p.w_uq + (size_t)l * 384 * 1536; ldsrc = 1536; K = 384; gain = p.q_norm + l * 384; dst = Wl + W_UQ; dld = 384; }
;       else if ((r -= 144) < 128)  { srcp = p.w_ukv + (size_t)l * 256 * 2048; ldsrc = 2048; K = 256; gain = p.kv_norm + l * 256; dst = Wl + W_UKV; dld = 256; }
;       else if ((r -= 128) < 256)  { srcp = p.w_o_mla + (size_t)l * 1024 * 1024; ldsrc = 1024; K = 1024; dst = Wl + W_OMLA; dld = 1024; }
;       else if ((r -= 256) < 128)  { srcp = p.w_fourier + (size_t)l * 512 * 1024; ldsrc = 1024; K = 512; dst = Wl + W_FOU; dld = 1024; }
;       else if ((r -= 128) < 128)  { srcp = p.w_o_mem + (size_t)l * 512 * 1024; ldsrc = 1024; K = 512; dst = Wl + W_FOU + 512; dld = 1024; }
;       else if ((r -= 128) < 256)  { srcp = p.w_out + (size_t)l * 1024 * 1024; ldsrc = 1024; K = 1024; dst = Wl + W_OUT; dld = 1024; }
.LBB0_23:
	s_ashr_i32 s29, s28, 31
	s_add_i32 s40, s40, s47
	s_lshl_b64 s[0:1], s[28:29], 1
	s_waitcnt vmcnt(0)
	ds_write_b32 v32, v6
	s_waitcnt lgkmcnt(0)
	s_barrier
	ds_read2_b32 v[72:73], v18 offset1:65
	ds_read2_b32 v[74:75], v20 offset1:65
	ds_read2_b32 v[76:77], v22 offset1:65
	ds_read2_b32 v[78:79], v24 offset1:65
	s_add_u32 s0, s26, s0
	v_add_u32_e32 v34, s40, v17
	s_addc_u32 s1, s27, s1
	s_waitcnt lgkmcnt(3)
	v_cvt_pk_bf16_f32 v33, v72, v73
	v_ashrrev_i32_e32 v6, 31, v34
	v_lshl_add_u64 v[8:9], s[0:1], 0, v[2:3]
	v_mul_lo_u32 v36, s24, v6
	v_mul_lo_u32 v37, s25, v34
	v_mad_u64_u32 v[34:35], s[0:1], s24, v34, 0
	v_add3_u32 v35, v35, v36, v37
	v_lshl_add_u64 v[34:35], v[34:35], 1, v[8:9]
	global_store_dword v[34:35], v33, off
	v_add_u32_e32 v34, s40, v19
	s_waitcnt lgkmcnt(2)
	v_cvt_pk_bf16_f32 v33, v74, v75
	v_ashrrev_i32_e32 v6, 31, v34
	v_mul_lo_u32 v36, s24, v6
	v_mul_lo_u32 v37, s25, v34
	v_mad_u64_u32 v[34:35], s[0:1], s24, v34, 0
	v_add3_u32 v35, v35, v36, v37
	v_lshl_add_u64 v[34:35], v[34:35], 1, v[8:9]
	global_store_dword v[34:35], v33, off
	v_add_u32_e32 v34, s40, v21
	s_waitcnt lgkmcnt(1)
	v_cvt_pk_bf16_f32 v33, v76, v77
	v_ashrrev_i32_e32 v6, 31, v34
	v_mul_lo_u32 v36, s24, v6
	v_mul_lo_u32 v37, s25, v34
	v_mad_u64_u32 v[34:35], s[0:1], s24, v34, 0
	v_add3_u32 v35, v35, v36, v37
	v_lshl_add_u64 v[34:35], v[34:35], 1, v[8:9]
	global_store_dword v[34:35], v33, off
	s_waitcnt lgkmcnt(0)
	v_cvt_pk_bf16_f32 v33, v78, v79
	v_add_u32_e32 v6, s40, v23
	v_ashrrev_i32_e32 v7, 31, v6
	v_mul_lo_u32 v34, s24, v7
	v_mul_lo_u32 v35, s25, v6
	v_mad_u64_u32 v[6:7], s[0:1], s24, v6, 0
	v_readlane_b32 s0, v253, 8
	v_add3_u32 v7, v7, v34, v35
	s_add_i32 s42, s42, s0
	v_lshl_add_u64 v[6:7], v[6:7], 1, v[8:9]
	s_cmpk_gt_i32 s42, 0x22ff
	global_store_dword v[6:7], v33, off
	s_cbranch_scc1 .LBB0_90

; __device__ __forceinline__ void tconv_tile(const float* __restrict__ src, int ldsrc, const float* __restrict__ gain, u16* __restrict__ dst, int dld,
;                                            int drow, int scol, int k0, int tid) {
;     ...
;   __syncthreads();
; #pragma unroll
;   for (int i = 0; i < 8; ++i) {
;     const int e = tid + i * NTHR, kk = e >> 6, nn = e & 63;
;     float v = src[(long)(k0 + kk) * ldsrc + scol + nn];
;     if (gain) v *= gain[k0 + kk];
;     tile[kk * 65 + nn] = v;
;   }
.LBB0_74:
	s_mul_i32 s1, s1, s46
	s_sub_i32 s1, s44, s1
	s_sext_i32_i16 s1, s1
	s_lshl_b32 s28, s1, 6
	s_ashr_i32 s1, s0, 31
	s_lshl_b64 s[0:1], s[0:1], 2
	s_add_u32 s0, s36, s0
	v_add_u32_e32 v8, s28, v1
	s_addc_u32 s1, s37, s1
	v_ashrrev_i32_e32 v9, 31, v8
	v_lshl_add_u64 v[6:7], s[0:1], 0, v[4:5]
	v_mul_lo_u32 v33, s34, v9
	v_mul_lo_u32 v36, s35, v8
	v_mad_u64_u32 v[34:35], s[0:1], s34, v8, 0
	v_add3_u32 v35, v35, v33, v36
	v_lshl_add_u64 v[34:35], v[34:35], 2, v[6:7]
	s_barrier
	s_cmp_eq_u64 s[22:23], 0
	s_cbranch_scc1 .Ltc_nogain
	v_add_u32_e32 v8, s28, v1
	v_ashrrev_i32_e32 v9, 31, v8
	v_lshl_add_u64 v[38:39], v[8:9], 2, s[22:23]
	global_load_dword v64, v[38:39], off
	v_mul_lo_u32 v33, s34, v9
	v_mul_lo_u32 v36, s35, v8
	v_mad_u64_u32 v[34:35], s[0:1], s34, v8, 0
	v_add3_u32 v35, v35, v33, v36
	v_lshl_add_u64 v[34:35], v[34:35], 2, v[6:7]
	global_load_dword v56, v[34:35], off
	v_add_u32_e32 v8, s28, v10
	v_ashrrev_i32_e32 v9, 31, v8
	v_lshl_add_u64 v[38:39], v[8:9], 2, s[22:23]
	global_load_dword v65, v[38:39], off
	v_mul_lo_u32 v33, s34, v9
	v_mul_lo_u32 v36, s35, v8
	v_mad_u64_u32 v[34:35], s[0:1], s34, v8, 0
	v_add3_u32 v35, v35, v33, v36
	v_lshl_add_u64 v[34:35], v[34:35], 2, v[6:7]
	global_load_dword v57, v[34:35], off
	v_add_u32_e32 v8, s28, v11
	v_ashrrev_i32_e32 v9, 31, v8
	v_lshl_add_u64 v[38:39], v[8:9], 2, s[22:23]
	global_load_dword v66, v[38:39], off
	v_mul_lo_u32 v33, s34, v9
	v_mul_lo_u32 v36, s35, v8
	v_mad_u64_u32 v[34:35], s[0:1], s34, v8, 0
	v_add3_u32 v35, v35, v33, v36
	v_lshl_add_u64 v[34:35], v[34:35], 2, v[6:7]
	global_load_dword v58, v[34:35], off
	v_add_u32_e32 v8, s28, v12
	v_ashrrev_i32_e32 v9, 31, v8
	v_lshl_add_u64 v[38:39], v[8:9], 2, s[22:23]
	global_load_dword v67, v[38:39], off
	v_mul_lo_u32 v33, s34, v9
	v_mul_lo_u32 v36, s35, v8
	v_mad_u64_u32 v[34:35], s[0:1], s34, v8, 0
	v_add3_u32 v35, v35, v33, v36
	v_lshl_add_u64 v[34:35], v[34:35], 2, v[6:7]
	global_load_dword v59, v[34:35], off
	v_add_u32_e32 v8, s28, v13
	v_ashrrev_i32_e32 v9, 31, v8
	v_lshl_add_u64 v[38:39], v[8:9], 2, s[22:23]
	global_load_dword v68, v[38:39], off
	v_mul_lo_u32 v33, s34, v9
	v_mul_lo_u32 v36, s35, v8
	v_mad_u64_u32 v[34:35], s[0:1], s34, v8, 0
	v_add3_u32 v35, v35, v33, v36
	v_lshl_add_u64 v[34:35], v[34:35], 2, v[6:7]
	global_load_dword v60, v[34:35], off
	v_add_u32_e32 v8, s28, v14
	v_ashrrev_i32_e32 v9, 31, v8
	v_lshl_add_u64 v[38:39], v[8:9], 2, s[22:23]
	global_load_dword v69, v[38:39], off
	v_mul_lo_u32 v33, s34, v9
	v_mul_lo_u32 v36, s35, v8
	v_mad_u64_u32 v[34:35], s[0:1], s34, v8, 0
	v_add3_u32 v35, v35, v33, v36
	v_lshl_add_u64 v[34:35], v[34:35], 2, v[6:7]
	global_load_dword v61, v[34:35], off
	v_add_u32_e32 v8, s28, v15
	v_ashrrev_i32_e32 v9, 31, v8
	v_lshl_add_u64 v[38:39], v[8:9], 2, s[22:23]
	global_load_dword v70, v[38:39], off
	v_mul_lo_u32 v33, s34, v9
	v_mul_lo_u32 v36, s35, v8
	v_mad_u64_u32 v[34:35], s[0:1], s34, v8, 0
	v_add3_u32 v35, v35, v33, v36
	v_lshl_add_u64 v[34:35], v[34:35], 2, v[6:7]
	global_load_dword v62, v[34:35], off
	v_add_u32_e32 v8, s28, v16
	v_ashrrev_i32_e32 v9, 31, v8
	v_lshl_add_u64 v[38:39], v[8:9], 2, s[22:23]
	global_load_dword v71, v[38:39], off
	v_mul_lo_u32 v33, s34, v9
	v_mul_lo_u32 v36, s35, v8
	v_mad_u64_u32 v[34:35], s[0:1], s34, v8, 0
	v_add3_u32 v35, v35, v33, v36
	v_lshl_add_u64 v[34:35], v[34:35], 2, v[6:7]
	global_load_dword v63, v[34:35], off
	s_waitcnt vmcnt(0)
	v_mul_f32_e32 v56, v56, v64
	v_mul_f32_e32 v57, v57, v65
	v_mul_f32_e32 v58, v58, v66
	v_mul_f32_e32 v59, v59, v67
	v_mul_f32_e32 v60, v60, v68
	v_mul_f32_e32 v61, v61, v69
	v_mul_f32_e32 v62, v62, v70
	v_mul_f32_e32 v63, v63, v71
	s_branch .Ltc_write
.Ltc_nogain:
	v_add_u32_e32 v8, s28, v1
	v_ashrrev_i32_e32 v9, 31, v8
	v_mul_lo_u32 v33, s34, v9
	v_mul_lo_u32 v36, s35, v8
	v_mad_u64_u32 v[34:35], s[0:1], s34, v8, 0
	v_add3_u32 v35, v35, v33, v36
	v_lshl_add_u64 v[34:35], v[34:35], 2, v[6:7]
	global_load_dword v56, v[34:35], off
	v_add_u32_e32 v8, s28, v10
	v_ashrrev_i32_e32 v9, 31, v8
	v_mul_lo_u32 v33, s34, v9
	v_mul_lo_u32 v36, s35, v8
	v_mad_u64_u32 v[34:35], s[0:1], s34, v8, 0
	v_add3_u32 v35, v35, v33, v36
	v_lshl_add_u64 v[34:35], v[34:35], 2, v[6:7]
	global_load_dword v57, v[34:35], off
	v_add_u32_e32 v8, s28, v11
	v_ashrrev_i32_e32 v9, 31, v8
	v_mul_lo_u32 v33, s34, v9
	v_mul_lo_u32 v36, s35, v8
	v_mad_u64_u32 v[34:35], s[0:1], s34, v8, 0
	v_add3_u32 v35, v35, v33, v36
	v_lshl_add_u64 v[34:35], v[34:35], 2, v[6:7]
	global_load_dword v58, v[34:35], off
	v_add_u32_e32 v8, s28, v12
	v_ashrrev_i32_e32 v9, 31, v8
	v_mul_lo_u32 v33, s34, v9
	v_mul_lo_u32 v36, s35, v8
	v_mad_u64_u32 v[34:35], s[0:1], s34, v8, 0
	v_add3_u32 v35, v35, v33, v36
	v_lshl_add_u64 v[34:35], v[34:35], 2, v[6:7]
	global_load_dword v59, v[34:35], off
	v_add_u32_e32 v8, s28, v13
	v_ashrrev_i32_e32 v9, 31, v8
	v_mul_lo_u32 v33, s34, v9
	v_mul_lo_u32 v36, s35, v8
	v_mad_u64_u32 v[34:35], s[0:1], s34, v8, 0
	v_add3_u32 v35, v35, v33, v36
	v_lshl_add_u64 v[34:35], v[34:35], 2, v[6:7]
	global_load_dword v60, v[34:35], off
	v_add_u32_e32 v8, s28, v14
	v_ashrrev_i32_e32 v9, 31, v8
	v_mul_lo_u32 v33, s34, v9
	v_mul_lo_u32 v36, s35, v8
	v_mad_u64_u32 v[34:35], s[0:1], s34, v8, 0
	v_add3_u32 v35, v35, v33, v36
	v_lshl_add_u64 v[34:35], v[34:35], 2, v[6:7]
	global_load_dword v61, v[34:35], off
	v_add_u32_e32 v8, s28, v15
	v_ashrrev_i32_e32 v9, 31, v8
	v_mul_lo_u32 v33, s34, v9
	v_mul_lo_u32 v36, s35, v8
	v_mad_u64_u32 v[34:35], s[0:1], s34, v8, 0
	v_add3_u32 v35, v35, v33, v36
	v_lshl_add_u64 v[34:35], v[34:35], 2, v[6:7]
	global_load_dword v62, v[34:35], off
	v_add_u32_e32 v8, s28, v16
	v_ashrrev_i32_e32 v9, 31, v8
	v_mul_lo_u32 v33, s34, v9
	v_mul_lo_u32 v36, s35, v8
	v_mad_u64_u32 v[34:35], s[0:1], s34, v8, 0
	v_add3_u32 v35, v35, v33, v36
	v_lshl_add_u64 v[34:35], v[34:35], 2, v[6:7]
	global_load_dword v63, v[34:35], off
	s_waitcnt vmcnt(0)
.Ltc_write:
	ds_write_b32 v25, v56
	ds_write_b32 v26, v57
	ds_write_b32 v27, v58
	ds_write_b32 v28, v59
	ds_write_b32 v29, v60
	ds_write_b32 v30, v61
	ds_write_b32 v31, v62
	v_mov_b32_e32 v6, v63
	s_branch .LBB0_23
